# best_v1 + XCD-local tile order in two panel halves for gemm1/gemmG/gemm4 (smaller L2 working set)
# speedup vs baseline: 1.0301x; 1.0236x over previous
.LBB0_154:
	s_cmp_ge_u32 s3, 270
	s_cbranch_scc1 .Lto_h1_0
	s_mul_hi_u32 s98, s3, 0x38e38e39
	s_lshr_b32 s98, s98, 1
	s_mul_i32 s99, s98, 9
	s_sub_u32 s99, s3, s99
	s_branch .Lto_j_0
.Lto_h1_0:
	s_sub_u32 s99, s3, 270
	s_lshr_b32 s98, s99, 3
	s_and_b32 s99, s99, 7
	s_add_u32 s99, s99, 9
.Lto_j_0:
	s_mul_i32 s98, s98, 17
	s_add_u32 s98, s98, s99
	s_lshl_b32 s99, s98, 3
	s_or_b32 s99, s99, s84
	s_mul_hi_i32 s6, s98, 0x78787879
	s_lshr_b32 s7, s6, 31
	s_ashr_i32 s6, s6, 3
	s_add_i32 s6, s6, s7
	s_mul_i32 s7, s6, 0xffffffef
	s_add_i32 s7, s7, s98
	s_lshl_b32 s7, s7, 3
	s_or_b32 s8, s7, s84
	v_mov_b32_e32 v0, v174
	s_ashr_i32 s9, s8, 31
	s_lshl_b64 s[10:11], s[8:9], 18
	v_bfe_u32 v2, v0, 1, 3
	v_lshrrev_b32_e32 v3, 4, v0
	v_bfe_u32 v4, v0, 4, 2
	v_lshlrev_b32_e32 v5, 7, v0
	v_and_b32_e32 v6, 0x780, v5
	v_bitop3_b32 v3, v3, v2, 3 bitop3:0x6c
	v_bitop3_b32 v2, v4, v2, 4 bitop3:0x36
	s_add_u32 s10, s38, s10
	v_lshl_or_b32 v7, v3, 4, v6
	v_lshl_or_b32 v6, v2, 4, v6
	v_lshlrev_b32_e32 v2, 6, v0
	s_addc_u32 s11, s39, s11
	s_ashr_i32 s7, s6, 31
	v_lshlrev_b32_e32 v1, 8, v0
	v_and_b32_e32 v8, 0xffffe000, v2
	v_lshlrev_b32_e32 v2, 4, v0
	s_lshl_b64 s[12:13], s[6:7], 18
	v_and_b32_e32 v1, 0xfffff800, v1
	v_xor_b32_e32 v0, v2, v0
	s_movk_i32 s7, 0x70
	v_add_u32_e32 v100, 0, v2
	v_and_or_b32 v64, v0, s7, v1
	v_readfirstlane_b32 s7, v100
	v_add_u32_e32 v101, 0x1000, v100
	s_mov_b32 m0, s7
	v_readfirstlane_b32 s7, v101
	v_add_u32_e32 v102, 0x2000, v100
	global_load_lds_dwordx4 v64, s[10:11]
	v_add_u32_e32 v0, 0x10000, v64
	s_mov_b32 m0, s7
	v_readfirstlane_b32 s7, v102
	v_add_u32_e32 v103, 0x3000, v100
	global_load_lds_dwordx4 v0, s[10:11]
	v_add_u32_e32 v2, 0x20000, v64
	s_mov_b32 m0, s7
	v_readfirstlane_b32 s7, v103
	v_add_u32_e32 v104, 0x4000, v100
	s_add_u32 s12, s36, s12
	global_load_lds_dwordx4 v2, s[10:11]
	v_add_u32_e32 v4, 0x30000, v64
	s_mov_b32 m0, s7
	v_readfirstlane_b32 s7, v104
	v_add_u32_e32 v105, 0x5000, v100
	s_addc_u32 s13, s37, s13
	global_load_lds_dwordx4 v4, s[10:11]
	s_mov_b32 m0, s7
	v_readfirstlane_b32 s7, v105
	v_add_u32_e32 v106, 0x6000, v100
	global_load_lds_dwordx4 v64, s[12:13]
	s_mov_b32 m0, s7
	v_readfirstlane_b32 s7, v106
	v_add_u32_e32 v107, 0x7000, v100
	global_load_lds_dwordx4 v0, s[12:13]
	s_mov_b32 m0, s7
	v_readfirstlane_b32 s7, v107
	global_load_lds_dwordx4 v2, s[12:13]
	s_mov_b32 m0, s7
	s_mul_i32 s7, s6, 0x88
	global_load_lds_dwordx4 v4, s[12:13]
	s_sub_i32 s10, s99, s7
	s_ashr_i32 s11, s10, 31
	s_lshl_b64 s[10:11], s[10:11], 18
	v_and_b32_e32 v9, 0x2000, v5
	s_add_u32 s10, s38, s10
	v_mov_b32_e32 v1, v65
	v_mov_b32_e32 v3, v65
	v_mov_b32_e32 v5, v65
	v_add_u32_e32 v8, 0, v8
	v_add_u32_e32 v9, 0, v9
	s_addc_u32 s11, s39, s11
	v_lshl_add_u64 v[66:67], s[12:13], 0, v[64:65]
	v_lshl_add_u64 v[68:69], s[12:13], 0, v[0:1]
	v_lshl_add_u64 v[70:71], s[12:13], 0, v[2:3]
	v_lshl_add_u64 v[72:73], s[12:13], 0, v[4:5]
	v_lshl_add_u64 v[74:75], s[10:11], 0, v[64:65]
	v_lshl_add_u64 v[76:77], s[10:11], 0, v[0:1]
	v_lshl_add_u64 v[78:79], s[10:11], 0, v[2:3]
	v_lshl_add_u64 v[80:81], s[10:11], 0, v[4:5]
	s_mov_b64 s[10:11], 0
	v_add_u32_e32 v64, 0x8000, v100
	v_add_u32_e32 v108, 0x9000, v100
	v_add_u32_e32 v109, 0xa000, v100
	v_add_u32_e32 v110, 0xb000, v100
	v_add_u32_e32 v111, 0xc000, v100
	v_add_u32_e32 v112, 0xd000, v100
	v_add_u32_e32 v113, 0xe000, v100
	v_add_u32_e32 v114, 0xf000, v100
	v_add_u32_e32 v115, v8, v7
	v_add_u32_e32 v116, v9, v7
	v_add_u32_e32 v117, v8, v6
	v_add_u32_e32 v118, v9, v6
	s_mov_b32 s7, 0
	v_mov_b32_e32 v0, 0
	v_mov_b32_e32 v2, v65
	v_mov_b32_e32 v4, 0
	v_mov_b32_e32 v6, v65
	v_mov_b32_e32 v7, v65
	v_mov_b32_e32 v8, 0
	v_mov_b32_e32 v9, v65
	v_mov_b32_e32 v10, v65
	v_mov_b32_e32 v11, v65
	v_mov_b32_e32 v12, 0
	v_mov_b32_e32 v13, v65
	v_mov_b32_e32 v14, v65
	v_mov_b32_e32 v15, v65
	v_mov_b32_e32 v16, 0
	v_mov_b32_e32 v17, v65
	v_mov_b32_e32 v18, v65
	v_mov_b32_e32 v19, v65
	v_mov_b32_e32 v20, 0
	v_mov_b32_e32 v21, v65
	v_mov_b32_e32 v22, v65
	v_mov_b32_e32 v23, v65
	v_mov_b32_e32 v24, 0
	v_mov_b32_e32 v25, v65
	v_mov_b32_e32 v26, v65
	v_mov_b32_e32 v27, v65
	v_mov_b32_e32 v28, 0
	v_mov_b32_e32 v29, v65
	v_mov_b32_e32 v30, v65
	v_mov_b32_e32 v31, v65
	v_mov_b32_e32 v32, 0
	v_mov_b32_e32 v33, v65
	v_mov_b32_e32 v34, v65
	v_mov_b32_e32 v35, v65
	v_mov_b32_e32 v36, 0
	v_mov_b32_e32 v37, v65
	v_mov_b32_e32 v38, v65
	v_mov_b32_e32 v39, v65
	v_mov_b32_e32 v40, 0
	v_mov_b32_e32 v41, v65
	v_mov_b32_e32 v42, v65
	v_mov_b32_e32 v43, v65
	v_mov_b32_e32 v44, 0
	v_mov_b32_e32 v45, v65
	v_mov_b32_e32 v46, v65
	v_mov_b32_e32 v47, v65
	v_mov_b32_e32 v48, 0
	v_mov_b32_e32 v49, v65
	v_mov_b32_e32 v50, v65
	v_mov_b32_e32 v51, v65
	v_mov_b32_e32 v52, 0
	v_mov_b32_e32 v53, v65
	v_mov_b32_e32 v54, v65
	v_mov_b32_e32 v55, v65
	v_mov_b32_e32 v56, 0
	v_mov_b32_e32 v57, v65
	v_mov_b32_e32 v58, v65
	v_mov_b32_e32 v59, v65
	v_mov_b32_e32 v60, 0
	v_mov_b32_e32 v61, v65
	v_mov_b32_e32 v62, v65
	v_mov_b32_e32 v63, v65
	s_branch .LBB0_156

.LBB0_608:
	s_cmp_ge_u32 s3, 288
	s_cbranch_scc1 .Lto_h1_1
	s_mul_hi_u32 s98, s3, 0x38e38e39
	s_lshr_b32 s98, s98, 1
	s_mul_i32 s99, s98, 9
	s_sub_u32 s99, s3, s99
	s_branch .Lto_j_1
.Lto_h1_1:
	s_sub_u32 s99, s3, 288
	s_lshr_b32 s98, s99, 3
	s_and_b32 s99, s99, 7
	s_add_u32 s99, s99, 9
.Lto_j_1:
	s_mul_i32 s98, s98, 17
	s_add_u32 s98, s98, s99
	s_lshl_b32 s99, s98, 3
	s_or_b32 s99, s99, s88
	s_mul_hi_i32 s10, s98, 0x78787879
	s_lshr_b32 s11, s10, 31
	s_ashr_i32 s10, s10, 3
	s_add_i32 s10, s10, s11
	s_mul_i32 s11, s10, 0xffffffef
	s_add_i32 s11, s11, s98
	s_lshl_b32 s11, s11, 3
	s_or_b32 s12, s11, s88
	v_mov_b32_e32 v0, v174
	s_ashr_i32 s13, s12, 31
	s_lshl_b64 s[34:35], s[12:13], 18
	v_bfe_u32 v2, v0, 1, 3
	v_lshrrev_b32_e32 v3, 4, v0
	v_bfe_u32 v4, v0, 4, 2
	v_lshlrev_b32_e32 v5, 7, v0
	v_and_b32_e32 v6, 0x780, v5
	v_bitop3_b32 v3, v3, v2, 3 bitop3:0x6c
	v_bitop3_b32 v2, v4, v2, 4 bitop3:0x36
	s_add_u32 s34, s38, s34
	v_lshl_or_b32 v7, v3, 4, v6
	v_lshl_or_b32 v6, v2, 4, v6
	v_lshlrev_b32_e32 v2, 6, v0
	s_addc_u32 s35, s39, s35
	s_ashr_i32 s11, s10, 31
	v_lshlrev_b32_e32 v1, 8, v0
	v_and_b32_e32 v8, 0xffffe000, v2
	v_lshlrev_b32_e32 v2, 4, v0
	s_lshl_b64 s[84:85], s[10:11], 18
	v_and_b32_e32 v1, 0xfffff800, v1
	v_xor_b32_e32 v0, v2, v0
	s_movk_i32 s11, 0x70
	v_add_u32_e32 v100, 0, v2
	v_and_or_b32 v64, v0, s11, v1
	v_readfirstlane_b32 s11, v100
	v_add_u32_e32 v101, 0x1000, v100
	s_mov_b32 m0, s11
	v_readfirstlane_b32 s11, v101
	v_add_u32_e32 v102, 0x2000, v100
	global_load_lds_dwordx4 v64, s[34:35]
	v_add_u32_e32 v0, 0x10000, v64
	s_mov_b32 m0, s11
	v_readfirstlane_b32 s11, v102
	v_add_u32_e32 v103, 0x3000, v100
	global_load_lds_dwordx4 v0, s[34:35]
	v_add_u32_e32 v2, 0x20000, v64
	s_mov_b32 m0, s11
	v_readfirstlane_b32 s11, v103
	v_add_u32_e32 v104, 0x4000, v100
	s_add_u32 s86, s90, s84
	global_load_lds_dwordx4 v2, s[34:35]
	v_add_u32_e32 v4, 0x30000, v64
	s_mov_b32 m0, s11
	v_readfirstlane_b32 s11, v104
	v_add_u32_e32 v105, 0x5000, v100
	s_addc_u32 s87, s91, s85
	global_load_lds_dwordx4 v4, s[34:35]
	s_mov_b32 m0, s11
	v_readfirstlane_b32 s11, v105
	v_add_u32_e32 v106, 0x6000, v100
	global_load_lds_dwordx4 v64, s[86:87]
	s_mov_b32 m0, s11
	v_readfirstlane_b32 s11, v106
	v_add_u32_e32 v107, 0x7000, v100
	global_load_lds_dwordx4 v0, s[86:87]
	s_mov_b32 m0, s11
	v_readfirstlane_b32 s11, v107
	global_load_lds_dwordx4 v2, s[86:87]
	s_mov_b32 m0, s11
	s_mul_i32 s11, s10, 0x88
	global_load_lds_dwordx4 v4, s[86:87]
	s_sub_i32 s34, s99, s11
	s_ashr_i32 s35, s34, 31
	s_lshl_b64 s[34:35], s[34:35], 18
	s_add_u32 s34, s38, s34
	v_and_b32_e32 v9, 0x2000, v5
	v_mov_b32_e32 v1, v65
	v_mov_b32_e32 v3, v65
	v_mov_b32_e32 v5, v65
	s_addc_u32 s35, s39, s35
	v_lshl_add_u64 v[66:67], s[34:35], 0, v[64:65]
	v_lshl_add_u64 v[68:69], s[34:35], 0, v[0:1]
	v_lshl_add_u64 v[70:71], s[34:35], 0, v[2:3]
	v_lshl_add_u64 v[72:73], s[34:35], 0, v[4:5]
	s_add_u32 s34, s36, s84
	v_add_u32_e32 v8, 0, v8
	v_add_u32_e32 v9, 0, v9
	s_addc_u32 s35, s37, s85
	v_lshl_add_u64 v[74:75], s[34:35], 0, v[64:65]
	v_lshl_add_u64 v[76:77], s[34:35], 0, v[0:1]
	v_lshl_add_u64 v[78:79], s[34:35], 0, v[2:3]
	v_lshl_add_u64 v[80:81], s[34:35], 0, v[4:5]
	s_mov_b64 s[84:85], 0
	v_add_u32_e32 v64, 0x8000, v100
	v_add_u32_e32 v108, 0x9000, v100
	v_add_u32_e32 v109, 0xa000, v100
	v_add_u32_e32 v110, 0xb000, v100
	v_add_u32_e32 v111, 0xc000, v100
	v_add_u32_e32 v112, 0xd000, v100
	v_add_u32_e32 v113, 0xe000, v100
	v_add_u32_e32 v114, 0xf000, v100
	v_add_u32_e32 v115, v8, v7
	v_add_u32_e32 v116, v9, v7
	v_add_u32_e32 v117, v8, v6
	v_add_u32_e32 v118, v9, v6
	s_mov_b32 s11, 0
	v_mov_b32_e32 v0, 0
	v_mov_b32_e32 v2, v65
	v_mov_b32_e32 v4, 0
	v_mov_b32_e32 v6, v65
	v_mov_b32_e32 v7, v65
	v_mov_b32_e32 v8, 0
	v_mov_b32_e32 v9, v65
	v_mov_b32_e32 v10, v65
	v_mov_b32_e32 v11, v65
	v_mov_b32_e32 v12, 0
	v_mov_b32_e32 v13, v65
	v_mov_b32_e32 v14, v65
	v_mov_b32_e32 v15, v65
	v_mov_b32_e32 v16, 0
	v_mov_b32_e32 v17, v65
	v_mov_b32_e32 v18, v65
	v_mov_b32_e32 v19, v65
	v_mov_b32_e32 v20, 0
	v_mov_b32_e32 v21, v65
	v_mov_b32_e32 v22, v65
	v_mov_b32_e32 v23, v65
	v_mov_b32_e32 v24, 0
	v_mov_b32_e32 v25, v65
	v_mov_b32_e32 v26, v65
	v_mov_b32_e32 v27, v65
	v_mov_b32_e32 v28, 0
	v_mov_b32_e32 v29, v65
	v_mov_b32_e32 v30, v65
	v_mov_b32_e32 v31, v65
	v_mov_b32_e32 v32, 0
	v_mov_b32_e32 v33, v65
	v_mov_b32_e32 v34, v65
	v_mov_b32_e32 v35, v65
	v_mov_b32_e32 v36, 0
	v_mov_b32_e32 v37, v65
	v_mov_b32_e32 v38, v65
	v_mov_b32_e32 v39, v65
	v_mov_b32_e32 v40, 0
	v_mov_b32_e32 v41, v65
	v_mov_b32_e32 v42, v65
	v_mov_b32_e32 v43, v65
	v_mov_b32_e32 v44, 0
	v_mov_b32_e32 v45, v65
	v_mov_b32_e32 v46, v65
	v_mov_b32_e32 v47, v65
	v_mov_b32_e32 v48, 0
	v_mov_b32_e32 v49, v65
	v_mov_b32_e32 v50, v65
	v_mov_b32_e32 v51, v65
	v_mov_b32_e32 v52, 0
	v_mov_b32_e32 v53, v65
	v_mov_b32_e32 v54, v65
	v_mov_b32_e32 v55, v65
	v_mov_b32_e32 v56, 0
	v_mov_b32_e32 v57, v65
	v_mov_b32_e32 v58, v65
	v_mov_b32_e32 v59, v65
	v_mov_b32_e32 v60, 0
	v_mov_b32_e32 v61, v65
	v_mov_b32_e32 v62, v65
	v_mov_b32_e32 v63, v65
	s_branch .LBB0_610

.LBB0_882:
	s_cmp_ge_u32 s3, 396
	s_cbranch_scc1 .Lto_h1_2
	s_mul_hi_u32 s98, s3, 0x38e38e39
	s_lshr_b32 s98, s98, 1
	s_mul_i32 s99, s98, 9
	s_sub_u32 s99, s3, s99
	s_branch .Lto_j_2
.Lto_h1_2:
	s_sub_u32 s99, s3, 396
	s_lshr_b32 s98, s99, 3
	s_and_b32 s99, s99, 7
	s_add_u32 s99, s99, 9
.Lto_j_2:
	s_mul_i32 s98, s98, 17
	s_add_u32 s98, s98, s99
	s_lshl_b32 s99, s98, 3
	s_or_b32 s99, s99, s90
	s_mul_hi_i32 s10, s98, 0x78787879
	s_lshr_b32 s11, s10, 31
	s_ashr_i32 s10, s10, 3
	s_add_i32 s10, s10, s11
	s_mul_i32 s11, s10, 0xffffffef
	s_add_i32 s11, s11, s98
	s_lshl_b32 s11, s11, 3
	s_or_b32 s12, s11, s90
	v_mov_b32_e32 v0, v174
	s_ashr_i32 s13, s12, 31
	s_lshl_b64 s[34:35], s[12:13], 18
	v_bfe_u32 v2, v0, 1, 3
	v_lshrrev_b32_e32 v3, 4, v0
	v_bfe_u32 v4, v0, 4, 2
	v_lshlrev_b32_e32 v5, 7, v0
	v_and_b32_e32 v6, 0x780, v5
	v_bitop3_b32 v3, v3, v2, 3 bitop3:0x6c
	v_bitop3_b32 v2, v4, v2, 4 bitop3:0x36
	s_add_u32 s34, s38, s34
	v_lshl_or_b32 v7, v3, 4, v6
	v_lshl_or_b32 v6, v2, 4, v6
	v_lshlrev_b32_e32 v2, 6, v0
	s_addc_u32 s35, s39, s35
	s_ashr_i32 s11, s10, 31
	v_lshlrev_b32_e32 v1, 8, v0
	v_and_b32_e32 v8, 0xffffe000, v2
	v_lshlrev_b32_e32 v2, 4, v0
	s_lshl_b64 s[84:85], s[10:11], 18
	v_and_b32_e32 v1, 0xfffff800, v1
	v_xor_b32_e32 v0, v2, v0
	s_movk_i32 s11, 0x70
	v_add_u32_e32 v100, 0, v2
	v_and_or_b32 v64, v0, s11, v1
	v_readfirstlane_b32 s11, v100
	v_add_u32_e32 v101, 0x1000, v100
	s_mov_b32 m0, s11
	v_readfirstlane_b32 s11, v101
	v_add_u32_e32 v102, 0x2000, v100
	global_load_lds_dwordx4 v64, s[34:35]
	v_add_u32_e32 v0, 0x10000, v64
	s_mov_b32 m0, s11
	v_readfirstlane_b32 s11, v102
	v_add_u32_e32 v103, 0x3000, v100
	global_load_lds_dwordx4 v0, s[34:35]
	v_add_u32_e32 v2, 0x20000, v64
	s_mov_b32 m0, s11
	v_readfirstlane_b32 s11, v103
	v_add_u32_e32 v104, 0x4000, v100
	s_add_u32 s88, s92, s84
	global_load_lds_dwordx4 v2, s[34:35]
	v_add_u32_e32 v4, 0x30000, v64
	s_mov_b32 m0, s11
	v_readfirstlane_b32 s11, v104
	v_add_u32_e32 v105, 0x5000, v100
	s_addc_u32 s89, s93, s85
	global_load_lds_dwordx4 v4, s[34:35]
	s_mov_b32 m0, s11
	v_readfirstlane_b32 s11, v105
	v_add_u32_e32 v106, 0x6000, v100
	global_load_lds_dwordx4 v64, s[88:89]
	s_mov_b32 m0, s11
	v_readfirstlane_b32 s11, v106
	v_add_u32_e32 v107, 0x7000, v100
	global_load_lds_dwordx4 v0, s[88:89]
	s_mov_b32 m0, s11
	v_readfirstlane_b32 s11, v107
	global_load_lds_dwordx4 v2, s[88:89]
	s_mov_b32 m0, s11
	s_mul_i32 s11, s10, 0x88
	global_load_lds_dwordx4 v4, s[88:89]
	s_sub_i32 s34, s99, s11
	s_ashr_i32 s35, s34, 31
	s_lshl_b64 s[34:35], s[34:35], 18
	s_add_u32 s34, s38, s34
	v_and_b32_e32 v9, 0x2000, v5
	v_mov_b32_e32 v1, v65
	v_mov_b32_e32 v3, v65
	v_mov_b32_e32 v5, v65
	s_addc_u32 s35, s39, s35
	v_lshl_add_u64 v[66:67], s[34:35], 0, v[64:65]
	v_lshl_add_u64 v[68:69], s[34:35], 0, v[0:1]
	v_lshl_add_u64 v[70:71], s[34:35], 0, v[2:3]
	v_lshl_add_u64 v[72:73], s[34:35], 0, v[4:5]
	s_add_u32 s34, s36, s84
	v_add_u32_e32 v8, 0, v8
	v_add_u32_e32 v9, 0, v9
	s_addc_u32 s35, s37, s85
	v_lshl_add_u64 v[74:75], s[34:35], 0, v[64:65]
	v_lshl_add_u64 v[76:77], s[34:35], 0, v[0:1]
	v_lshl_add_u64 v[78:79], s[34:35], 0, v[2:3]
	v_lshl_add_u64 v[80:81], s[34:35], 0, v[4:5]
	s_mov_b64 s[84:85], 0
	v_add_u32_e32 v64, 0x8000, v100
	v_add_u32_e32 v108, 0x9000, v100
	v_add_u32_e32 v109, 0xa000, v100
	v_add_u32_e32 v110, 0xb000, v100
	v_add_u32_e32 v111, 0xc000, v100
	v_add_u32_e32 v112, 0xd000, v100
	v_add_u32_e32 v113, 0xe000, v100
	v_add_u32_e32 v114, 0xf000, v100
	v_add_u32_e32 v115, v8, v7
	v_add_u32_e32 v116, v9, v7
	v_add_u32_e32 v117, v8, v6
	v_add_u32_e32 v118, v9, v6
	s_mov_b32 s11, 0
	v_mov_b32_e32 v0, 0
	v_mov_b32_e32 v2, v65
	v_mov_b32_e32 v8, 0
	v_mov_b32_e32 v9, v65
	v_mov_b32_e32 v10, v65
	v_mov_b32_e32 v11, v65
	v_mov_b32_e32 v4, 0
	v_mov_b32_e32 v6, v65
	v_mov_b32_e32 v7, v65
	v_mov_b32_e32 v12, 0
	v_mov_b32_e32 v13, v65
	v_mov_b32_e32 v14, v65
	v_mov_b32_e32 v15, v65
	v_mov_b32_e32 v16, 0
	v_mov_b32_e32 v17, v65
	v_mov_b32_e32 v18, v65
	v_mov_b32_e32 v19, v65
	v_mov_b32_e32 v24, 0
	v_mov_b32_e32 v25, v65
	v_mov_b32_e32 v26, v65
	v_mov_b32_e32 v27, v65
	v_mov_b32_e32 v20, 0
	v_mov_b32_e32 v21, v65
	v_mov_b32_e32 v22, v65
	v_mov_b32_e32 v23, v65
	v_mov_b32_e32 v28, 0
	v_mov_b32_e32 v29, v65
	v_mov_b32_e32 v30, v65
	v_mov_b32_e32 v31, v65
	v_mov_b32_e32 v32, 0
	v_mov_b32_e32 v33, v65
	v_mov_b32_e32 v34, v65
	v_mov_b32_e32 v35, v65
	v_mov_b32_e32 v40, 0
	v_mov_b32_e32 v41, v65
	v_mov_b32_e32 v42, v65
	v_mov_b32_e32 v43, v65
	v_mov_b32_e32 v36, 0
	v_mov_b32_e32 v37, v65
	v_mov_b32_e32 v38, v65
	v_mov_b32_e32 v39, v65
	v_mov_b32_e32 v44, 0
	v_mov_b32_e32 v45, v65
	v_mov_b32_e32 v46, v65
	v_mov_b32_e32 v47, v65
	v_mov_b32_e32 v48, 0
	v_mov_b32_e32 v49, v65
	v_mov_b32_e32 v50, v65
	v_mov_b32_e32 v51, v65
	v_mov_b32_e32 v56, 0
	v_mov_b32_e32 v57, v65
	v_mov_b32_e32 v58, v65
	v_mov_b32_e32 v59, v65
	v_mov_b32_e32 v52, 0
	v_mov_b32_e32 v53, v65
	v_mov_b32_e32 v54, v65
	v_mov_b32_e32 v55, v65
	v_mov_b32_e32 v60, 0
	v_mov_b32_e32 v61, v65
	v_mov_b32_e32 v62, v65
	v_mov_b32_e32 v63, v65
	s_branch .LBB0_884

.Lto_j_3:
	s_mul_i32 s98, s98, 17
	s_add_u32 s98, s98, s99
	s_lshl_b32 s99, s98, 3
	s_or_b32 s99, s99, s18
	s_mul_hi_i32 s6, s98, 0x78787879
	s_lshr_b32 s7, s6, 31
	s_ashr_i32 s6, s6, 3
	s_add_i32 s6, s6, s7
	s_mul_i32 s7, s6, 0xffffffef
	s_add_i32 s7, s7, s98
	s_lshl_b32 s7, s7, 3
	s_or_b32 s8, s7, s18
	v_mov_b32_e32 v0, v174
	s_ashr_i32 s9, s8, 31
	s_lshl_b64 s[10:11], s[8:9], 18
	v_bfe_u32 v2, v0, 1, 3
	v_lshrrev_b32_e32 v3, 4, v0
	v_bfe_u32 v4, v0, 4, 2
	v_lshlrev_b32_e32 v5, 7, v0
	v_and_b32_e32 v6, 0x780, v5
	v_bitop3_b32 v3, v3, v2, 3 bitop3:0x6c
	v_bitop3_b32 v2, v4, v2, 4 bitop3:0x36
	s_add_u32 s10, s38, s10
	v_lshl_or_b32 v7, v3, 4, v6
	v_lshl_or_b32 v6, v2, 4, v6
	v_lshlrev_b32_e32 v2, 6, v0
	s_addc_u32 s11, s39, s11
	s_ashr_i32 s7, s6, 31
	v_lshlrev_b32_e32 v1, 8, v0
	v_and_b32_e32 v8, 0xffffe000, v2
	v_lshlrev_b32_e32 v2, 4, v0
	s_lshl_b64 s[12:13], s[6:7], 18
	v_and_b32_e32 v1, 0xfffff800, v1
	v_xor_b32_e32 v0, v2, v0
	s_movk_i32 s7, 0x70
	v_add_u32_e32 v100, 0, v2
	v_and_or_b32 v64, v0, s7, v1
	v_readfirstlane_b32 s7, v100
	v_add_u32_e32 v101, 0x1000, v100
	s_mov_b32 m0, s7
	v_readfirstlane_b32 s7, v101
	v_add_u32_e32 v102, 0x2000, v100
	global_load_lds_dwordx4 v64, s[10:11]
	v_add_u32_e32 v0, 0x10000, v64
	s_mov_b32 m0, s7
	v_readfirstlane_b32 s7, v102
	v_add_u32_e32 v103, 0x3000, v100
	global_load_lds_dwordx4 v0, s[10:11]
	v_add_u32_e32 v2, 0x20000, v64
	s_mov_b32 m0, s7
	v_readfirstlane_b32 s7, v103
	v_add_u32_e32 v104, 0x4000, v100
	s_add_u32 s12, s36, s12
	global_load_lds_dwordx4 v2, s[10:11]
	v_add_u32_e32 v4, 0x30000, v64
	s_mov_b32 m0, s7
	v_readfirstlane_b32 s7, v104
	v_add_u32_e32 v105, 0x5000, v100
	s_addc_u32 s13, s37, s13
	global_load_lds_dwordx4 v4, s[10:11]
	s_mov_b32 m0, s7
	v_readfirstlane_b32 s7, v105
	v_add_u32_e32 v106, 0x6000, v100
	global_load_lds_dwordx4 v64, s[12:13]
	s_mov_b32 m0, s7
	v_readfirstlane_b32 s7, v106
	v_add_u32_e32 v107, 0x7000, v100
	global_load_lds_dwordx4 v0, s[12:13]
	s_mov_b32 m0, s7
	v_readfirstlane_b32 s7, v107
	global_load_lds_dwordx4 v2, s[12:13]
	s_mov_b32 m0, s7
	s_mul_i32 s7, s6, 0x88
	global_load_lds_dwordx4 v4, s[12:13]
	s_sub_i32 s10, s99, s7
	s_ashr_i32 s11, s10, 31
	s_lshl_b64 s[10:11], s[10:11], 18
	v_and_b32_e32 v9, 0x2000, v5
	s_add_u32 s10, s38, s10
	v_mov_b32_e32 v1, v65
	v_mov_b32_e32 v3, v65
	v_mov_b32_e32 v5, v65
	v_add_u32_e32 v8, 0, v8
	v_add_u32_e32 v9, 0, v9
	s_addc_u32 s11, s39, s11
	v_lshl_add_u64 v[66:67], s[12:13], 0, v[64:65]
	v_lshl_add_u64 v[68:69], s[12:13], 0, v[0:1]
	v_lshl_add_u64 v[70:71], s[12:13], 0, v[2:3]
	v_lshl_add_u64 v[72:73], s[12:13], 0, v[4:5]
	v_lshl_add_u64 v[74:75], s[10:11], 0, v[64:65]
	v_lshl_add_u64 v[76:77], s[10:11], 0, v[0:1]
	v_lshl_add_u64 v[78:79], s[10:11], 0, v[2:3]
	v_lshl_add_u64 v[80:81], s[10:11], 0, v[4:5]
	s_mov_b64 s[10:11], 0
	v_add_u32_e32 v64, 0x8000, v100
	v_add_u32_e32 v108, 0x9000, v100
	v_add_u32_e32 v109, 0xa000, v100
	v_add_u32_e32 v110, 0xb000, v100
	v_add_u32_e32 v111, 0xc000, v100
	v_add_u32_e32 v112, 0xd000, v100
	v_add_u32_e32 v113, 0xe000, v100
	v_add_u32_e32 v114, 0xf000, v100
	v_add_u32_e32 v115, v8, v7
	v_add_u32_e32 v116, v9, v7
	v_add_u32_e32 v117, v8, v6
	v_add_u32_e32 v118, v9, v6
	s_mov_b32 s7, 0
	v_mov_b32_e32 v0, 0
	v_mov_b32_e32 v2, v65
	v_mov_b32_e32 v4, 0
	v_mov_b32_e32 v6, v65
	v_mov_b32_e32 v7, v65
	v_mov_b32_e32 v8, 0
	v_mov_b32_e32 v9, v65
	v_mov_b32_e32 v10, v65
	v_mov_b32_e32 v11, v65
	v_mov_b32_e32 v12, 0
	v_mov_b32_e32 v13, v65
	v_mov_b32_e32 v14, v65
	v_mov_b32_e32 v15, v65
	v_mov_b32_e32 v16, 0
	v_mov_b32_e32 v17, v65
	v_mov_b32_e32 v18, v65
	v_mov_b32_e32 v19, v65
	v_mov_b32_e32 v20, 0
	v_mov_b32_e32 v21, v65
	v_mov_b32_e32 v22, v65
	v_mov_b32_e32 v23, v65
	v_mov_b32_e32 v24, 0
	v_mov_b32_e32 v25, v65
	v_mov_b32_e32 v26, v65
	v_mov_b32_e32 v27, v65
	v_mov_b32_e32 v28, 0
	v_mov_b32_e32 v29, v65
	v_mov_b32_e32 v30, v65
	v_mov_b32_e32 v31, v65
	v_mov_b32_e32 v32, 0
	v_mov_b32_e32 v33, v65
	v_mov_b32_e32 v34, v65
	v_mov_b32_e32 v35, v65
	v_mov_b32_e32 v36, 0
	v_mov_b32_e32 v37, v65
	v_mov_b32_e32 v38, v65
	v_mov_b32_e32 v39, v65
	v_mov_b32_e32 v40, 0
	v_mov_b32_e32 v41, v65
	v_mov_b32_e32 v42, v65
	v_mov_b32_e32 v43, v65
	v_mov_b32_e32 v44, 0
	v_mov_b32_e32 v45, v65
	v_mov_b32_e32 v46, v65
	v_mov_b32_e32 v47, v65
	v_mov_b32_e32 v48, 0
	v_mov_b32_e32 v49, v65
	v_mov_b32_e32 v50, v65
	v_mov_b32_e32 v51, v65
	v_mov_b32_e32 v52, 0
	v_mov_b32_e32 v53, v65
	v_mov_b32_e32 v54, v65
	v_mov_b32_e32 v55, v65
	v_mov_b32_e32 v56, 0
	v_mov_b32_e32 v57, v65
	v_mov_b32_e32 v58, v65
	v_mov_b32_e32 v59, v65
	v_mov_b32_e32 v60, 0
	v_mov_b32_e32 v61, v65
	v_mov_b32_e32 v62, v65
	v_mov_b32_e32 v63, v65
	s_branch .LBB0_1142

.Lto_j_4:
	s_mul_i32 s98, s98, 17
	s_add_u32 s98, s98, s99
	s_lshl_b32 s99, s98, 3
	s_or_b32 s99, s99, s20
	s_mul_hi_i32 s10, s98, 0x78787879
	s_lshr_b32 s11, s10, 31
	s_ashr_i32 s10, s10, 3
	s_add_i32 s10, s10, s11
	s_mul_i32 s11, s10, 0xffffffef
	s_add_i32 s11, s11, s98
	s_lshl_b32 s11, s11, 3
	v_mov_b32_e32 v0, v174
	s_or_b32 s12, s11, s20
	s_ashr_i32 s13, s12, 31
	v_bfe_u32 v2, v0, 1, 3
	v_lshrrev_b32_e32 v3, 4, v0
	v_bfe_u32 v4, v0, 4, 2
	v_lshlrev_b32_e32 v5, 7, v0
	v_and_b32_e32 v6, 0x780, v5
	v_bitop3_b32 v3, v3, v2, 3 bitop3:0x6c
	v_bitop3_b32 v2, v4, v2, 4 bitop3:0x36
	s_lshl_b64 s[16:17], s[12:13], 18
	v_lshl_or_b32 v7, v3, 4, v6
	v_lshl_or_b32 v6, v2, 4, v6
	v_lshlrev_b32_e32 v2, 6, v0
	s_add_u32 s16, s38, s16
	v_and_b32_e32 v8, 0xffffe000, v2
	v_lshlrev_b32_e32 v2, 4, v0
	s_addc_u32 s17, s39, s17
	s_ashr_i32 s11, s10, 31
	v_lshlrev_b32_e32 v1, 8, v0
	v_add_u32_e32 v100, 0, v2
	s_lshl_b64 s[18:19], s[10:11], 18
	v_and_b32_e32 v1, 0xfffff800, v1
	v_xor_b32_e32 v0, v2, v0
	v_readfirstlane_b32 s11, v100
	v_add_u32_e32 v101, 0x1000, v100
	v_and_or_b32 v64, v0, s27, v1
	s_mov_b32 m0, s11
	v_readfirstlane_b32 s11, v101
	v_add_u32_e32 v102, 0x2000, v100
	global_load_lds_dwordx4 v64, s[16:17]
	v_add_u32_e32 v0, 0x10000, v64
	s_mov_b32 m0, s11
	v_readfirstlane_b32 s11, v102
	v_add_u32_e32 v103, 0x3000, v100
	global_load_lds_dwordx4 v0, s[16:17]
	v_add_u32_e32 v2, 0x20000, v64
	s_mov_b32 m0, s11
	v_readfirstlane_b32 s11, v103
	v_add_u32_e32 v104, 0x4000, v100
	s_add_u32 s34, s24, s18
	global_load_lds_dwordx4 v2, s[16:17]
	v_add_u32_e32 v4, 0x30000, v64
	s_mov_b32 m0, s11
	v_readfirstlane_b32 s11, v104
	v_add_u32_e32 v105, 0x5000, v100
	s_addc_u32 s35, s25, s19
	global_load_lds_dwordx4 v4, s[16:17]
	s_mov_b32 m0, s11
	v_readfirstlane_b32 s11, v105
	v_add_u32_e32 v106, 0x6000, v100
	global_load_lds_dwordx4 v64, s[34:35]
	s_mov_b32 m0, s11
	v_readfirstlane_b32 s11, v106
	v_add_u32_e32 v107, 0x7000, v100
	global_load_lds_dwordx4 v0, s[34:35]
	s_mov_b32 m0, s11
	v_readfirstlane_b32 s11, v107
	global_load_lds_dwordx4 v2, s[34:35]
	s_mov_b32 m0, s11
	s_mul_i32 s11, s10, 0x88
	global_load_lds_dwordx4 v4, s[34:35]
	s_sub_i32 s16, s99, s11
	s_ashr_i32 s17, s16, 31
	s_lshl_b64 s[16:17], s[16:17], 18
	s_add_u32 s16, s38, s16
	v_and_b32_e32 v9, 0x2000, v5
	v_mov_b32_e32 v1, v65
	v_mov_b32_e32 v3, v65
	v_mov_b32_e32 v5, v65
	s_addc_u32 s17, s39, s17
	v_lshl_add_u64 v[66:67], s[16:17], 0, v[64:65]
	v_lshl_add_u64 v[68:69], s[16:17], 0, v[0:1]
	v_lshl_add_u64 v[70:71], s[16:17], 0, v[2:3]
	v_lshl_add_u64 v[72:73], s[16:17], 0, v[4:5]
	s_add_u32 s16, s36, s18
	v_add_u32_e32 v8, 0, v8
	v_add_u32_e32 v9, 0, v9
	s_addc_u32 s17, s37, s19
	v_lshl_add_u64 v[74:75], s[16:17], 0, v[64:65]
	v_lshl_add_u64 v[76:77], s[16:17], 0, v[0:1]
	v_lshl_add_u64 v[78:79], s[16:17], 0, v[2:3]
	v_lshl_add_u64 v[80:81], s[16:17], 0, v[4:5]
	s_mov_b64 s[16:17], 0
	v_add_u32_e32 v64, 0x8000, v100
	v_add_u32_e32 v108, 0x9000, v100
	v_add_u32_e32 v109, 0xa000, v100
	v_add_u32_e32 v110, 0xb000, v100
	v_add_u32_e32 v111, 0xc000, v100
	v_add_u32_e32 v112, 0xd000, v100
	v_add_u32_e32 v113, 0xe000, v100
	v_add_u32_e32 v114, 0xf000, v100
	v_add_u32_e32 v115, v8, v7
	v_add_u32_e32 v116, v9, v7
	v_add_u32_e32 v117, v8, v6
	v_add_u32_e32 v118, v9, v6
	s_mov_b32 s11, 0
	v_mov_b32_e32 v0, 0
	v_mov_b32_e32 v2, v65
	v_mov_b32_e32 v4, 0
	v_mov_b32_e32 v6, v65
	v_mov_b32_e32 v7, v65
	v_mov_b32_e32 v8, 0
	v_mov_b32_e32 v9, v65
	v_mov_b32_e32 v10, v65
	v_mov_b32_e32 v11, v65
	v_mov_b32_e32 v12, 0
	v_mov_b32_e32 v13, v65
	v_mov_b32_e32 v14, v65
	v_mov_b32_e32 v15, v65
	v_mov_b32_e32 v16, 0
	v_mov_b32_e32 v17, v65
	v_mov_b32_e32 v18, v65
	v_mov_b32_e32 v19, v65
	v_mov_b32_e32 v20, 0
	v_mov_b32_e32 v21, v65
	v_mov_b32_e32 v22, v65
	v_mov_b32_e32 v23, v65
	v_mov_b32_e32 v24, 0
	v_mov_b32_e32 v25, v65
	v_mov_b32_e32 v26, v65
	v_mov_b32_e32 v27, v65
	v_mov_b32_e32 v28, 0
	v_mov_b32_e32 v29, v65
	v_mov_b32_e32 v30, v65
	v_mov_b32_e32 v31, v65
	v_mov_b32_e32 v32, 0
	v_mov_b32_e32 v33, v65
	v_mov_b32_e32 v34, v65
	v_mov_b32_e32 v35, v65
	v_mov_b32_e32 v36, 0
	v_mov_b32_e32 v37, v65
	v_mov_b32_e32 v38, v65
	v_mov_b32_e32 v39, v65
	v_mov_b32_e32 v40, 0
	v_mov_b32_e32 v41, v65
	v_mov_b32_e32 v42, v65
	v_mov_b32_e32 v43, v65
	v_mov_b32_e32 v44, 0
	v_mov_b32_e32 v45, v65
	v_mov_b32_e32 v46, v65
	v_mov_b32_e32 v47, v65
	v_mov_b32_e32 v48, 0
	v_mov_b32_e32 v49, v65
	v_mov_b32_e32 v50, v65
	v_mov_b32_e32 v51, v65
	v_mov_b32_e32 v52, 0
	v_mov_b32_e32 v53, v65
	v_mov_b32_e32 v54, v65
	v_mov_b32_e32 v55, v65
	v_mov_b32_e32 v56, 0
	v_mov_b32_e32 v57, v65
	v_mov_b32_e32 v58, v65
	v_mov_b32_e32 v59, v65
	v_mov_b32_e32 v60, 0
	v_mov_b32_e32 v61, v65
	v_mov_b32_e32 v62, v65
	v_mov_b32_e32 v63, v65
	s_branch .LBB0_1593

.Lto_j_5:
	s_mul_i32 s98, s98, 17
	s_add_u32 s98, s98, s99
	s_lshl_b32 s99, s98, 3
	s_or_b32 s99, s99, s20
	s_mul_hi_i32 s10, s98, 0x78787879
	s_lshr_b32 s11, s10, 31
	s_ashr_i32 s10, s10, 3
	s_add_i32 s10, s10, s11
	s_mul_i32 s11, s10, 0xffffffef
	s_add_i32 s11, s11, s98
	s_lshl_b32 s11, s11, 3
	v_mov_b32_e32 v0, v174
	s_or_b32 s12, s11, s20
	s_ashr_i32 s13, s12, 31
	v_bfe_u32 v2, v0, 1, 3
	v_lshrrev_b32_e32 v3, 4, v0
	v_bfe_u32 v4, v0, 4, 2
	v_lshlrev_b32_e32 v5, 7, v0
	v_and_b32_e32 v6, 0x780, v5
	v_bitop3_b32 v3, v3, v2, 3 bitop3:0x6c
	v_bitop3_b32 v2, v4, v2, 4 bitop3:0x36
	s_lshl_b64 s[16:17], s[12:13], 18
	v_lshl_or_b32 v7, v3, 4, v6
	v_lshl_or_b32 v6, v2, 4, v6
	v_lshlrev_b32_e32 v2, 6, v0
	s_add_u32 s16, s38, s16
	v_and_b32_e32 v8, 0xffffe000, v2
	v_lshlrev_b32_e32 v2, 4, v0
	s_addc_u32 s17, s39, s17
	s_ashr_i32 s11, s10, 31
	v_lshlrev_b32_e32 v1, 8, v0
	v_add_u32_e32 v100, 0, v2
	s_lshl_b64 s[18:19], s[10:11], 18
	v_and_b32_e32 v1, 0xfffff800, v1
	v_xor_b32_e32 v0, v2, v0
	v_readfirstlane_b32 s11, v100
	v_add_u32_e32 v101, 0x1000, v100
	v_and_or_b32 v64, v0, s25, v1
	s_mov_b32 m0, s11
	v_readfirstlane_b32 s11, v101
	v_add_u32_e32 v102, 0x2000, v100
	global_load_lds_dwordx4 v64, s[16:17]
	v_add_u32_e32 v0, 0x10000, v64
	s_mov_b32 m0, s11
	v_readfirstlane_b32 s11, v102
	v_add_u32_e32 v103, 0x3000, v100
	global_load_lds_dwordx4 v0, s[16:17]
	v_add_u32_e32 v2, 0x20000, v64
	s_mov_b32 m0, s11
	v_readfirstlane_b32 s11, v103
	v_add_u32_e32 v104, 0x4000, v100
	s_add_u32 s34, s22, s18
	global_load_lds_dwordx4 v2, s[16:17]
	v_add_u32_e32 v4, 0x30000, v64
	s_mov_b32 m0, s11
	v_readfirstlane_b32 s11, v104
	v_add_u32_e32 v105, 0x5000, v100
	s_addc_u32 s35, s23, s19
	global_load_lds_dwordx4 v4, s[16:17]
	s_mov_b32 m0, s11
	v_readfirstlane_b32 s11, v105
	v_add_u32_e32 v106, 0x6000, v100
	global_load_lds_dwordx4 v64, s[34:35]
	s_mov_b32 m0, s11
	v_readfirstlane_b32 s11, v106
	v_add_u32_e32 v107, 0x7000, v100
	global_load_lds_dwordx4 v0, s[34:35]
	s_mov_b32 m0, s11
	v_readfirstlane_b32 s11, v107
	global_load_lds_dwordx4 v2, s[34:35]
	s_mov_b32 m0, s11
	s_mul_i32 s11, s10, 0x88
	global_load_lds_dwordx4 v4, s[34:35]
	s_sub_i32 s16, s99, s11
	s_ashr_i32 s17, s16, 31
	s_lshl_b64 s[16:17], s[16:17], 18
	s_add_u32 s16, s38, s16
	v_and_b32_e32 v9, 0x2000, v5
	v_mov_b32_e32 v1, v65
	v_mov_b32_e32 v3, v65
	v_mov_b32_e32 v5, v65
	s_addc_u32 s17, s39, s17
	v_lshl_add_u64 v[66:67], s[16:17], 0, v[64:65]
	v_lshl_add_u64 v[68:69], s[16:17], 0, v[0:1]
	v_lshl_add_u64 v[70:71], s[16:17], 0, v[2:3]
	v_lshl_add_u64 v[72:73], s[16:17], 0, v[4:5]
	s_add_u32 s16, s36, s18
	v_add_u32_e32 v8, 0, v8
	v_add_u32_e32 v9, 0, v9
	s_addc_u32 s17, s37, s19
	v_lshl_add_u64 v[74:75], s[16:17], 0, v[64:65]
	v_lshl_add_u64 v[76:77], s[16:17], 0, v[0:1]
	v_lshl_add_u64 v[78:79], s[16:17], 0, v[2:3]
	v_lshl_add_u64 v[80:81], s[16:17], 0, v[4:5]
	s_mov_b64 s[16:17], 0
	v_add_u32_e32 v64, 0x8000, v100
	v_add_u32_e32 v108, 0x9000, v100
	v_add_u32_e32 v109, 0xa000, v100
	v_add_u32_e32 v110, 0xb000, v100
	v_add_u32_e32 v111, 0xc000, v100
	v_add_u32_e32 v112, 0xd000, v100
	v_add_u32_e32 v113, 0xe000, v100
	v_add_u32_e32 v114, 0xf000, v100
	v_add_u32_e32 v115, v8, v7
	v_add_u32_e32 v116, v9, v7
	v_add_u32_e32 v117, v8, v6
	v_add_u32_e32 v118, v9, v6
	s_mov_b32 s11, 0
	v_mov_b32_e32 v0, 0
	v_mov_b32_e32 v2, v65
	v_mov_b32_e32 v8, 0
	v_mov_b32_e32 v9, v65
	v_mov_b32_e32 v10, v65
	v_mov_b32_e32 v11, v65
	v_mov_b32_e32 v4, 0
	v_mov_b32_e32 v6, v65
	v_mov_b32_e32 v7, v65
	v_mov_b32_e32 v12, 0
	v_mov_b32_e32 v13, v65
	v_mov_b32_e32 v14, v65
	v_mov_b32_e32 v15, v65
	v_mov_b32_e32 v16, 0
	v_mov_b32_e32 v17, v65
	v_mov_b32_e32 v18, v65
	v_mov_b32_e32 v19, v65
	v_mov_b32_e32 v24, 0
	v_mov_b32_e32 v25, v65
	v_mov_b32_e32 v26, v65
	v_mov_b32_e32 v27, v65
	v_mov_b32_e32 v20, 0
	v_mov_b32_e32 v21, v65
	v_mov_b32_e32 v22, v65
	v_mov_b32_e32 v23, v65
	v_mov_b32_e32 v28, 0
	v_mov_b32_e32 v29, v65
	v_mov_b32_e32 v30, v65
	v_mov_b32_e32 v31, v65
	v_mov_b32_e32 v32, 0
	v_mov_b32_e32 v33, v65
	v_mov_b32_e32 v34, v65
	v_mov_b32_e32 v35, v65
	v_mov_b32_e32 v40, 0
	v_mov_b32_e32 v41, v65
	v_mov_b32_e32 v42, v65
	v_mov_b32_e32 v43, v65
	v_mov_b32_e32 v36, 0
	v_mov_b32_e32 v37, v65
	v_mov_b32_e32 v38, v65
	v_mov_b32_e32 v39, v65
	v_mov_b32_e32 v44, 0
	v_mov_b32_e32 v45, v65
	v_mov_b32_e32 v46, v65
	v_mov_b32_e32 v47, v65
	v_mov_b32_e32 v48, 0
	v_mov_b32_e32 v49, v65
	v_mov_b32_e32 v50, v65
	v_mov_b32_e32 v51, v65
	v_mov_b32_e32 v56, 0
	v_mov_b32_e32 v57, v65
	v_mov_b32_e32 v58, v65
	v_mov_b32_e32 v59, v65
	v_mov_b32_e32 v52, 0
	v_mov_b32_e32 v53, v65
	v_mov_b32_e32 v54, v65
	v_mov_b32_e32 v55, v65
	v_mov_b32_e32 v60, 0
	v_mov_b32_e32 v61, v65
	v_mov_b32_e32 v62, v65
	v_mov_b32_e32 v63, v65
	s_branch .LBB0_1867
